# band attention: unclipped-bias tiles use one address + ds_read2_b32 pairs instead of per-element clamp/address/ds_read
# speedup vs baseline: 1.0064x; 1.0031x over previous
.LBB0_946:
	s_or_b64 exec, exec, s[18:19]
	ds_read_b32 v0, v205 offset:2048
	v_add_u32_e32 v186, s0, v217
	v_cmp_ge_i32_e64 s[38:39], v186, v218
	v_add_u32_e32 v225, v216, v221
	s_and_saveexec_b64 s[4:5], s[38:39]
	s_xor_b64 s[18:19], exec, s[4:5]
	s_cbranch_execz .LBB0_948
	v_cmp_gt_i32_e32 vcc, 0x101, v225
	s_cmp_eq_u64 vcc, exec
	s_cbranch_scc1 .Lattn_fast0
	v_add_u32_e32 v187, -1, v225
	v_med3_i32 v186, v225, s63, v202
	v_med3_i32 v187, v187, s63, v202
	v_add_u32_e32 v188, -2, v225
	v_add_u32_e32 v189, -3, v225
	v_lshl_add_u32 v186, v186, 2, v205
	v_lshl_add_u32 v187, v187, 2, v205
	v_med3_i32 v188, v188, s63, v202
	v_med3_i32 v189, v189, s63, v202
	ds_read_b32 v186, v186 offset:1024
	ds_read_b32 v187, v187 offset:1024
	v_lshl_add_u32 v188, v188, 2, v205
	v_lshl_add_u32 v189, v189, 2, v205
	ds_read_b32 v188, v188 offset:1024
	ds_read_b32 v189, v189 offset:1024
	v_add_u32_e32 v191, -5, v225
	v_subrev_u32_e32 v195, 17, v225
	v_med3_i32 v191, v191, s63, v202
	v_med3_i32 v195, v195, s63, v202
	v_lshl_add_u32 v191, v191, 2, v205
	v_lshl_add_u32 v195, v195, 2, v205
	ds_read_b32 v191, v191 offset:1024
	ds_read_b32 v195, v195 offset:1024
	s_waitcnt lgkmcnt(4)
	v_pk_add_f32 v[186:187], v[82:83], v[186:187]
	s_waitcnt lgkmcnt(2)
	v_pk_add_f32 v[188:189], v[84:85], v[188:189]
	v_max_f32_e32 v190, 0xf149f2ca, v186
	v_max3_f32 v192, v190, v187, v188
	v_add_u32_e32 v190, -4, v225
	v_med3_i32 v190, v190, s63, v202
	v_lshl_add_u32 v190, v190, 2, v205
	ds_read_b32 v190, v190 offset:1024
	v_add_u32_e32 v193, -7, v225
	v_subrev_u32_e32 v199, 21, v225
	v_med3_i32 v193, v193, s63, v202
	v_med3_i32 v199, v199, s63, v202
	v_lshl_add_u32 v193, v193, 2, v205
	v_lshl_add_u32 v199, v199, 2, v205
	ds_read_b32 v193, v193 offset:1024
	ds_read_b32 v199, v199 offset:1024
	s_waitcnt lgkmcnt(2)
	v_pk_add_f32 v[190:191], v[86:87], v[190:191]
	v_subrev_u32_e32 v197, 19, v225
	v_max3_f32 v194, v192, v189, v190
	v_add_u32_e32 v192, -6, v225
	v_med3_i32 v192, v192, s63, v202
	v_lshl_add_u32 v192, v192, 2, v205
	ds_read_b32 v192, v192 offset:1024
	v_med3_i32 v197, v197, s63, v202
	v_lshl_add_u32 v197, v197, 2, v205
	ds_read_b32 v197, v197 offset:1024
	s_waitcnt lgkmcnt(1)
	v_pk_add_f32 v[192:193], v[88:89], v[192:193]
	s_nop 0
	v_max3_f32 v196, v194, v191, v192
	v_add_u32_e32 v194, -16, v225
	v_med3_i32 v194, v194, s63, v202
	v_lshl_add_u32 v194, v194, 2, v205
	ds_read_b32 v194, v194 offset:1024
	s_waitcnt lgkmcnt(0)
	v_pk_add_f32 v[194:195], v[90:91], v[194:195]
	s_nop 0
	v_max3_f32 v198, v196, v193, v194
	v_subrev_u32_e32 v196, 18, v225
	v_med3_i32 v196, v196, s63, v202
	v_lshl_add_u32 v196, v196, 2, v205
	ds_read_b32 v196, v196 offset:1024
	s_waitcnt lgkmcnt(0)
	v_pk_add_f32 v[196:197], v[92:93], v[196:197]
	s_nop 0
	v_max3_f32 v224, v198, v195, v196
	v_subrev_u32_e32 v198, 20, v225
	v_med3_i32 v198, v198, s63, v202
	v_lshl_add_u32 v198, v198, 2, v205
	ds_read_b32 v198, v198 offset:1024
	s_waitcnt lgkmcnt(0)
	v_pk_add_f32 v[198:199], v[94:95], v[198:199]
	s_nop 0
	v_max3_f32 v226, v224, v197, v198
	v_subrev_u32_e32 v224, 22, v225
	v_med3_i32 v224, v224, s63, v202
	v_lshl_add_u32 v224, v224, 2, v205
	ds_read_b32 v224, v224 offset:1024
	s_waitcnt lgkmcnt(0)
	v_add_f32_e32 v224, v96, v224
	v_max3_f32 v227, v226, v199, v224
	v_subrev_u32_e32 v226, 23, v225
	v_med3_i32 v226, v226, s63, v202
	v_lshl_add_u32 v226, v226, 2, v205
	ds_read_b32 v226, v226 offset:1024

.LBB0_952:
	s_and_saveexec_b64 s[4:5], s[38:39]
	s_xor_b64 s[18:19], exec, s[4:5]
	s_cbranch_execz .LBB0_954
	v_cmp_gt_i32_e32 vcc, 0xe1, v225
	s_cmp_eq_u64 vcc, exec
	s_cbranch_scc1 .Lattn_fast1
	v_add_u32_e32 v0, 32, v225
	v_med3_i32 v0, v0, s63, v202
	v_lshl_add_u32 v0, v0, 2, v205
	ds_read_b32 v82, v0 offset:1024
	v_add_u32_e32 v0, 31, v225
	v_med3_i32 v0, v0, s63, v202
	v_lshl_add_u32 v0, v0, 2, v205
	ds_read_b32 v83, v0 offset:1024
	s_waitcnt lgkmcnt(0)
	v_pk_add_f32 v[84:85], v[66:67], v[82:83]
	v_add_u32_e32 v66, 30, v225
	v_add_u32_e32 v67, 29, v225
	v_med3_i32 v66, v66, s63, v202
	v_med3_i32 v67, v67, s63, v202
	v_lshl_add_u32 v66, v66, 2, v205
	v_lshl_add_u32 v67, v67, 2, v205
	ds_read_b32 v66, v66 offset:1024
	ds_read_b32 v67, v67 offset:1024
	v_max3_f32 v0, v84, s48, v85
	s_waitcnt lgkmcnt(0)
	v_pk_add_f32 v[86:87], v[68:69], v[66:67]
	v_add_u32_e32 v66, 28, v225
	v_add_u32_e32 v67, 27, v225
	v_med3_i32 v66, v66, s63, v202
	v_med3_i32 v67, v67, s63, v202
	v_lshl_add_u32 v66, v66, 2, v205
	v_lshl_add_u32 v67, v67, 2, v205
	ds_read_b32 v66, v66 offset:1024
	ds_read_b32 v67, v67 offset:1024
	v_max3_f32 v0, v0, v86, v87
	s_waitcnt lgkmcnt(0)
	v_pk_add_f32 v[82:83], v[70:71], v[66:67]
	v_add_u32_e32 v66, 26, v225
	v_add_u32_e32 v67, 25, v225
	v_med3_i32 v66, v66, s63, v202
	v_med3_i32 v67, v67, s63, v202
	v_lshl_add_u32 v66, v66, 2, v205
	v_lshl_add_u32 v67, v67, 2, v205
	ds_read_b32 v66, v66 offset:1024
	ds_read_b32 v67, v67 offset:1024
	v_max3_f32 v0, v0, v82, v83
	s_waitcnt lgkmcnt(0)
	v_pk_add_f32 v[88:89], v[72:73], v[66:67]
	v_add_u32_e32 v66, 16, v225
	v_add_u32_e32 v67, 15, v225
	v_med3_i32 v66, v66, s63, v202
	v_med3_i32 v67, v67, s63, v202
	v_lshl_add_u32 v66, v66, 2, v205
	v_lshl_add_u32 v67, v67, 2, v205
	ds_read_b32 v66, v66 offset:1024
	ds_read_b32 v67, v67 offset:1024
	v_max3_f32 v0, v0, v88, v89
	s_waitcnt lgkmcnt(0)
	v_pk_add_f32 v[90:91], v[74:75], v[66:67]
	v_add_u32_e32 v66, 14, v225
	v_add_u32_e32 v67, 13, v225
	v_med3_i32 v66, v66, s63, v202
	v_med3_i32 v67, v67, s63, v202
	v_lshl_add_u32 v66, v66, 2, v205
	v_lshl_add_u32 v67, v67, 2, v205
	ds_read_b32 v66, v66 offset:1024
	ds_read_b32 v67, v67 offset:1024
	v_max3_f32 v0, v0, v90, v91
	s_waitcnt lgkmcnt(0)
	v_pk_add_f32 v[92:93], v[76:77], v[66:67]
	v_add_u32_e32 v66, 12, v225
	v_add_u32_e32 v67, 11, v225
	v_med3_i32 v66, v66, s63, v202
	v_med3_i32 v67, v67, s63, v202
	v_lshl_add_u32 v66, v66, 2, v205
	v_lshl_add_u32 v67, v67, 2, v205
	ds_read_b32 v66, v66 offset:1024
	ds_read_b32 v67, v67 offset:1024
	v_max3_f32 v0, v0, v92, v93
	s_waitcnt lgkmcnt(0)
	v_pk_add_f32 v[94:95], v[78:79], v[66:67]
	v_add_u32_e32 v66, 10, v225
	v_add_u32_e32 v67, 9, v225
	v_med3_i32 v66, v66, s63, v202
	v_med3_i32 v67, v67, s63, v202
	v_lshl_add_u32 v66, v66, 2, v205
	v_lshl_add_u32 v67, v67, 2, v205
	ds_read_b32 v66, v66 offset:1024
	ds_read_b32 v67, v67 offset:1024
	v_max3_f32 v0, v0, v94, v95
	s_waitcnt lgkmcnt(0)
	v_pk_add_f32 v[96:97], v[80:81], v[66:67]
	s_nop 0
	v_max3_f32 v228, v0, v96, v97

.Lattn_fast0:
	v_lshl_add_u32 v227, v225, 2, v205
	v_add_u32_e32 v227, 0x3a4, v227
	ds_read2_b32 v[186:187], v227 offset0:23 offset1:22
	ds_read2_b32 v[188:189], v227 offset0:21 offset1:20
	ds_read2_b32 v[190:191], v227 offset0:19 offset1:18
	ds_read2_b32 v[192:193], v227 offset0:17 offset1:16
	ds_read2_b32 v[194:195], v227 offset0:7 offset1:6
	ds_read2_b32 v[196:197], v227 offset0:5 offset1:4
	ds_read2_b32 v[198:199], v227 offset0:3 offset1:2
	ds_read_b32 v224, v227 offset:4
	ds_read_b32 v226, v227
	s_waitcnt lgkmcnt(0)
	v_pk_add_f32 v[186:187], v[82:83], v[186:187]
	v_pk_add_f32 v[188:189], v[84:85], v[188:189]
	v_pk_add_f32 v[190:191], v[86:87], v[190:191]
	v_pk_add_f32 v[192:193], v[88:89], v[192:193]
	v_pk_add_f32 v[194:195], v[90:91], v[194:195]
	v_pk_add_f32 v[196:197], v[92:93], v[196:197]
	v_pk_add_f32 v[198:199], v[94:95], v[198:199]
	v_add_f32_e32 v224, v96, v224
	v_max_f32_e32 v227, 0xf149f2ca, v186
	v_max3_f32 v227, v227, v187, v188
	v_max3_f32 v227, v227, v189, v190
	v_max3_f32 v227, v227, v191, v192
	v_max3_f32 v227, v227, v193, v194
	v_max3_f32 v227, v227, v195, v196
	v_max3_f32 v227, v227, v197, v198
	v_max3_f32 v227, v227, v199, v224
	s_branch .LBB0_948
.Lattn_fast1:
	v_lshl_add_u32 v0, v225, 2, v205
	v_add_u32_e32 v0, 0x424, v0
	ds_read2_b32 v[84:85], v0 offset0:23 offset1:22
	ds_read2_b32 v[86:87], v0 offset0:21 offset1:20
	ds_read2_b32 v[82:83], v0 offset0:19 offset1:18
	ds_read2_b32 v[88:89], v0 offset0:17 offset1:16
	ds_read2_b32 v[90:91], v0 offset0:7 offset1:6
	ds_read2_b32 v[92:93], v0 offset0:5 offset1:4
	ds_read2_b32 v[94:95], v0 offset0:3 offset1:2
	ds_read2_b32 v[96:97], v0 offset0:1 offset1:0
	s_waitcnt lgkmcnt(0)
	v_pk_add_f32 v[84:85], v[66:67], v[84:85]
	v_pk_add_f32 v[86:87], v[68:69], v[86:87]
	v_pk_add_f32 v[82:83], v[70:71], v[82:83]
	v_pk_add_f32 v[88:89], v[72:73], v[88:89]
	v_pk_add_f32 v[90:91], v[74:75], v[90:91]
	v_pk_add_f32 v[92:93], v[76:77], v[92:93]
	v_pk_add_f32 v[94:95], v[78:79], v[94:95]
	v_pk_add_f32 v[96:97], v[80:81], v[96:97]
	v_max3_f32 v0, v84, s48, v85
	v_max3_f32 v0, v0, v86, v87
	v_max3_f32 v0, v0, v82, v83
	v_max3_f32 v0, v0, v88, v89
	v_max3_f32 v0, v0, v90, v91
	v_max3_f32 v0, v0, v92, v93
	v_max3_f32 v0, v0, v94, v95
	v_max3_f32 v228, v0, v96, v97
	s_branch .LBB0_954
